# MLA fast loop row sums: two 32-term serial v_add_f32 chains replaced by v_pk_add_f32 on aligned register pairs (f32, reassociated)
# speedup vs baseline: 1.0393x; 1.0103x over previous
.Lf_966:
	s_or_b64 exec, exec, s[44:45]
	v_pk_add_f32 v[244:245], v[88:89], v[90:91]
	v_pk_add_f32 v[246:247], v[92:93], v[94:95]
	v_pk_add_f32 v[244:245], v[244:245], v[112:113]
	v_pk_add_f32 v[246:247], v[246:247], v[114:115]
	v_pk_add_f32 v[244:245], v[244:245], v[116:117]
	v_pk_add_f32 v[246:247], v[246:247], v[118:119]
	v_pk_add_f32 v[244:245], v[244:245], v[120:121]
	v_pk_add_f32 v[246:247], v[246:247], v[122:123]
	v_pk_add_f32 v[244:245], v[244:245], v[124:125]
	v_pk_add_f32 v[246:247], v[246:247], v[126:127]
	v_pk_add_f32 v[244:245], v[244:245], v[140:141]
	v_pk_add_f32 v[246:247], v[246:247], v[142:143]
	v_pk_add_f32 v[244:245], v[244:245], v[246:247]
	v_add_f32_e32 v248, v244, v245
	v_add_f32_e32 v248, v80, v248
	v_add_f32_e32 v248, v87, v248
	v_add_f32_e32 v248, v106, v248
	v_add_f32_e32 v248, v139, v248
	v_add_f32_e32 v206, v206, v248
	v_pk_add_f32 v[244:245], v[12:13], v[14:15]
	v_pk_add_f32 v[246:247], v[82:83], v[84:85]
	v_pk_add_f32 v[244:245], v[244:245], v[96:97]
	v_pk_add_f32 v[246:247], v[246:247], v[98:99]
	v_pk_add_f32 v[244:245], v[244:245], v[100:101]
	v_pk_add_f32 v[246:247], v[246:247], v[102:103]
	v_pk_add_f32 v[244:245], v[244:245], v[104:105]
	v_pk_add_f32 v[246:247], v[246:247], v[128:129]
	v_pk_add_f32 v[244:245], v[244:245], v[130:131]
	v_pk_add_f32 v[246:247], v[246:247], v[132:133]
	v_pk_add_f32 v[244:245], v[244:245], v[134:135]
	v_pk_add_f32 v[246:247], v[246:247], v[136:137]
	v_pk_add_f32 v[244:245], v[244:245], v[246:247]
	s_mulk_i32 s6, 0x2400
	v_add_f32_e32 v248, v244, v245
	v_add_f32_e32 v248, v11, v248
	v_add_f32_e32 v248, v86, v248
	v_add_f32_e32 v248, v138, v248
	v_add_f32_e32 v248, v237, v248
	v_add_f32_e32 v0, v0, v248
	v_add_u32_e32 v2, s6, v215
	v_lshl_add_u64 v[200:201], v[200:201], 0, s[10:11]
	s_cmp_eq_u32 s33, 63
	v_lshl_add_u64 v[202:203], v[202:203], 0, s[12:13]
	s_waitcnt vmcnt(0)
	ds_write_b128 v2, v[6:9] offset:26624
	s_waitcnt lgkmcnt(0)
	s_barrier
	s_cbranch_scc1 .LBB0_970
	s_mov_b32 s24, s33
	s_branch .Lf_960
